# group-local hand-offs (GEMM <-> row-op chains) synchronise with an 8-block group barrier instead of the grid barrier when the run-time XCD check passes
# speedup vs baseline: 1.0243x; 1.0146x over previous
_Z2mk1Pii:
	s_load_dwordx4 s[44:47], s[0:1], 0x190
	s_add_u32 s4, s0, 0x198
	s_addc_u32 s5, s1, 0
	v_writelane_b32 v164, s2, 0
	v_writelane_b32 v162, 0, 60
	v_writelane_b32 v162, 0, 62
	v_writelane_b32 v162, 0, 63
	s_waitcnt lgkmcnt(0)
	s_cmp_lt_i32 s45, 0
	s_cbranch_scc1 .LBB0_2
	v_and_b32_e32 v128, 0x3ff, v0
	s_load_dword s33, s[0:1], 0x1a0
	s_cbranch_execz .LBB0_3
	s_branch .LBB0_14

.LBB0_152:
	s_waitcnt vmcnt(0) lgkmcnt(0)
	v_mov_b32_e32 v1, 0
	v_mov_b32_e32 v3, 1
	v_readlane_b32 s20, v162, 62
	v_readlane_b32 s21, v164, 0
	v_readlane_b32 s22, v162, 63
	s_cmp_eq_u32 s20, 1
	s_cbranch_scc0 .Lxb21_glob
	s_and_b32 s4, s21, 15
	s_lshl_b32 s4, s4, 8
	s_bfe_u32 s5, s21, 0x20004
	s_lshl_b32 s5, s5, 5
	s_add_u32 s4, s4, s5
	s_add_u32 s4, s4, 0x480
	s_add_u32 s4, s84, s4
	s_addc_u32 s5, s85, 0
	s_add_u32 s22, s22, 1
	s_nop 1
	v_writelane_b32 v162, s22, 63
	s_lshl_b32 s22, s22, 3
	global_atomic_add v1, v3, s[4:5]
	s_mov_b32 s20, 0
.Lxb21_gspin:
	global_load_dword v0, v1, s[4:5] sc1
	s_waitcnt vmcnt(0)
	v_readfirstlane_b32 s21, v0
	s_cmp_ge_u32 s21, s22
	s_cbranch_scc1 .Lxb21_done
	s_sleep 1
	s_add_u32 s20, s20, 1
	s_cmp_lt_u32 s20, 0x400000
	s_cbranch_scc1 .Lxb21_gspin
	s_branch .Lxb21_done
.Lxb21_glob:
	v_readlane_b32 s20, v162, 60
	s_lshl_b32 s2, s40, 8
	s_add_u32 s2, s84, s2
	s_addc_u32 s3, s85, 0
	s_add_u32 s2, s2, 0x1440
	s_addc_u32 s3, s3, 0
	s_add_u32 s20, s20, 1
	s_nop 2
	v_writelane_b32 v162, s20, 60
	global_atomic_add v4, v1, v3, s[2:3] sc0
	v_mul_lo_u32 v2, v2, s20
	v_mul_lo_u32 v0, v0, s20
	s_add_u32 s22, s84, 0x3440
	s_addc_u32 s23, s85, 0
	s_waitcnt vmcnt(0)
	v_add_u32_e32 v4, 1, v4
	s_nop 0
	v_cmp_eq_u32_e32 vcc, v4, v2
	s_nop 3
	s_cbranch_vccz .Lxb21_poll
	v_readlane_b32 s21, v162, 62
	s_nop 1
	s_cmp_eq_u32 s21, 1
	s_cbranch_scc1 .Lxb21_nowb
	buffer_wbl2 sc1
	s_waitcnt vmcnt(0)

.Lxb0_ninv:
	s_barrier
	s_and_saveexec_b64 s[2:3], s[4:5]
	s_cbranch_execz .LBB0_246
	s_waitcnt vmcnt(0) lgkmcnt(0)
	v_readlane_b32 s20, v162, 62
	v_readlane_b32 s21, v164, 0
	v_readlane_b32 s22, v162, 63
	s_cmp_eq_u32 s20, 1
	s_cbranch_scc0 .Lxb0_glob
	s_and_b32 s4, s21, 15
	s_lshl_b32 s4, s4, 8
	s_bfe_u32 s5, s21, 0x20004
	s_lshl_b32 s5, s5, 5
	s_add_u32 s4, s4, s5
	s_add_u32 s4, s4, 0x480
	s_add_u32 s4, s84, s4
	s_addc_u32 s5, s85, 0
	s_add_u32 s22, s22, 1
	s_nop 1
	v_writelane_b32 v162, s22, 63
	s_lshl_b32 s22, s22, 3
	global_atomic_add v117, v129, s[4:5]
	s_mov_b32 s20, 0
.Lxb0_gspin:
	global_load_dword v0, v117, s[4:5] sc1
	s_waitcnt vmcnt(0)
	v_readfirstlane_b32 s21, v0
	s_cmp_ge_u32 s21, s22
	s_cbranch_scc1 .Lxb0_done
	s_sleep 1
	s_add_u32 s20, s20, 1
	s_cmp_lt_u32 s20, 0x400000
	s_cbranch_scc1 .Lxb0_gspin
	s_branch .Lxb0_done
.Lxb0_glob:
	ds_read_b32 v2, v117 offset:53248
	ds_read_b32 v3, v117 offset:53252
	v_readlane_b32 s4, v163, 62
	v_readlane_b32 s5, v163, 63
	v_readlane_b32 s36, v162, 60
	s_nop 1
	s_add_u32 s36, s36, 1
	s_nop 2
	v_writelane_b32 v162, s36, 60
	global_atomic_add v0, v117, v129, s[4:5] offset:64 sc0
	s_waitcnt lgkmcnt(0)
	v_lshrrev_b32_e32 v4, 1, v2
	v_mul_lo_u32 v2, v2, s36
	v_mul_lo_u32 v3, v3, s36
	v_readlane_b32 s4, v162, 2
	v_readlane_b32 s5, v162, 3
	s_waitcnt vmcnt(0)
	v_add_u32_e32 v0, 1, v0
	s_nop 0
	v_cmp_eq_u32_e32 vcc, v0, v2
	s_nop 3
	s_cbranch_vccz .Lxb0_poll
	v_readlane_b32 s20, v162, 62
	s_nop 1
	s_cmp_eq_u32 s20, 1
	s_cbranch_scc1 .Lxb0_nowb
	buffer_wbl2 sc1
	s_waitcnt vmcnt(0)

.LBB0_1123:
	s_waitcnt vmcnt(0) lgkmcnt(0)
	v_readlane_b32 s20, v162, 62
	v_readlane_b32 s21, v164, 0
	v_readlane_b32 s22, v162, 63
	s_cmp_eq_u32 s20, 1
	s_cbranch_scc0 .Lxb11_glob
	s_and_b32 s4, s21, 15
	s_lshl_b32 s4, s4, 8
	s_bfe_u32 s5, s21, 0x20004
	s_lshl_b32 s5, s5, 5
	s_add_u32 s4, s4, s5
	s_add_u32 s4, s4, 0x480
	s_add_u32 s4, s84, s4
	s_addc_u32 s5, s85, 0
	s_add_u32 s22, s22, 1
	s_nop 1
	v_writelane_b32 v162, s22, 63
	s_lshl_b32 s22, s22, 3
	global_atomic_add v117, v129, s[4:5]
	s_mov_b32 s20, 0
